# c2 + one static s_setprio 1 for waves 0-3 (older half) around each GEMM K-loop, per-segment flips deleted
# baseline (speedup 1.0000x reference)
; #define PG8_STAGE(bufoff, gbase, voff) do { _Pragma("unroll") for (int _i = 0; _i < 2; ++_i) \
;         __builtin_amdgcn_global_load_lds((const unsigned*)((const char*)(gbase) + (voff)[_i]), (PG8_LAS unsigned*)(lds + (bufoff) + ldsw + _i * 8192), 16, 0, 0); } while (0)
; #define PG8_WAIT_V(n) asm volatile("s_waitcnt vmcnt(" #n ")" ::: "memory")
; #define PG8_BAR __builtin_amdgcn_s_barrier()
; template <class Epi>
; __device__ __forceinline__ void gemm_phase(PG8_LAS unsigned char* lds, const Gemm g, const StaticOrder& S, const Epi& E) {
;     ...
;     f32x4 acc[2][2][4][2];
; #pragma unroll
;     for (int a = 0; a < 2; ++a)
; #pragma unroll
;         for (int b = 0; b < 2; ++b)
; #pragma unroll
;             for (int m = 0; m < 4; ++m)
; #pragma unroll
;                 for (int n = 0; n < 2; ++n) acc[a][b][m][n] = (f32x4){0.f, 0.f, 0.f, 0.f};
;     bf16x8 At[4][2], B0[2][2], B1[2][2];
;     const char* cA = (const char*)g.A + (size_t)cur.pm * tstepA; const char* cB = (const char*)g.Bt + (size_t)cur.pn * tstepB;
;     PG8_STAGE(PG8_SB(0, 0), cB, voffB); PG8_STAGE(PG8_SA(0, 0), cA, voffA); PG8_STAGE(PG8_SB(0, 1), cB + hstepB, voffB); PG8_STAGE(PG8_SA(0, 1), cA + hstepA, voffA);
;     if (wr == 1) PG8_BAR;
;     PG8_WAIT_V(4); PG8_BAR;
;     PG8_STAGE(PG8_SB(1, 0), cB + kstep, voffB); PG8_STAGE(PG8_SA(1, 0), cA + kstep, voffA); PG8_STAGE(PG8_SB(1, 1), cB + hstepB + kstep, voffB);
;     PG8_WAIT_V(6); PG8_BAR;
;     for (;;) {
;         const bool has_next = S.next(ui + 1, nxt);
;         const char* nA = has_next ? (const char*)g.A + (size_t)nxt.pm * tstepA : cA; const char* nB = has_next ? (const char*)g.Bt + (size_t)nxt.pn * tstepB : cB;
;         for (int t = 0; t < nt; t += 2) {
;             const bool last = (t == nt - 2);
;             const char* a1 = cA + (size_t)(t + 1) * kstep;
;             const char* a2 = last ? nA : cA + (size_t)(t + 2) * kstep; const char* b2 = last ? nB : cB + (size_t)(t + 2) * kstep;
.LBB0_225:
	s_ashr_i32 s53, s52, 31
	v_cmp_lt_i64_e32 vcc, s[6:7], v[152:153]
	s_lshl_b64 s[6:7], s[52:53], 20
	s_add_u32 s56, s76, s6
	s_addc_u32 s57, s77, s7
	s_and_b64 s[6:7], vcc, exec
	s_cselect_b32 s47, s57, s1
	s_cselect_b32 s49, s56, s0
	s_ashr_i32 s51, s50, 31
	s_lshl_b64 s[6:7], s[50:51], 20
	s_add_u32 s58, s80, s6
	s_addc_u32 s59, s81, s7
	s_and_b64 s[6:7], vcc, exec
	s_cselect_b32 s51, s59, s5
	s_cselect_b32 s53, s58, s4
	s_add_u32 s0, s0, 0x80080
	s_addc_u32 s1, s1, 0
	s_add_u32 s60, s4, 0x100
	v_mov_b32_e32 v8, 0
	s_addc_u32 s61, s5, 0
	s_mov_b32 s62, -2
	v_mov_b32_e32 v9, v8
	v_mov_b32_e32 v10, v8
	v_mov_b32_e32 v11, v8
	v_mov_b32_e32 v16, v8
	v_mov_b32_e32 v17, v8
	v_mov_b32_e32 v18, v8
	v_mov_b32_e32 v19, v8
	v_mov_b32_e32 v24, v8
	v_mov_b32_e32 v25, v8
	v_mov_b32_e32 v26, v8
	v_mov_b32_e32 v27, v8
	v_mov_b32_e32 v32, v8
	v_mov_b32_e32 v33, v8
	v_mov_b32_e32 v34, v8
	v_mov_b32_e32 v35, v8
	v_mov_b32_e32 v40, v8
	v_mov_b32_e32 v41, v8
	v_mov_b32_e32 v42, v8
	v_mov_b32_e32 v43, v8
	v_mov_b32_e32 v48, v8
	v_mov_b32_e32 v49, v8
	v_mov_b32_e32 v50, v8
	v_mov_b32_e32 v51, v8
	v_mov_b32_e32 v56, v8
	v_mov_b32_e32 v57, v8
	v_mov_b32_e32 v58, v8
	v_mov_b32_e32 v59, v8
	v_mov_b32_e32 v64, v8
	v_mov_b32_e32 v65, v8
	v_mov_b32_e32 v66, v8
	v_mov_b32_e32 v67, v8
	v_mov_b32_e32 v12, v8
	v_mov_b32_e32 v13, v8
	v_mov_b32_e32 v14, v8
	v_mov_b32_e32 v15, v8
	v_mov_b32_e32 v20, v8
	v_mov_b32_e32 v21, v8
	v_mov_b32_e32 v22, v8
	v_mov_b32_e32 v23, v8
	v_mov_b32_e32 v28, v8
	v_mov_b32_e32 v29, v8
	v_mov_b32_e32 v30, v8
	v_mov_b32_e32 v31, v8
	v_mov_b32_e32 v36, v8
	v_mov_b32_e32 v37, v8
	v_mov_b32_e32 v38, v8
	v_mov_b32_e32 v39, v8
	v_mov_b32_e32 v44, v8
	v_mov_b32_e32 v45, v8
	v_mov_b32_e32 v46, v8
	v_mov_b32_e32 v47, v8
	v_mov_b32_e32 v52, v8
	v_mov_b32_e32 v53, v8
	v_mov_b32_e32 v54, v8
	v_mov_b32_e32 v55, v8
	v_mov_b32_e32 v60, v8
	v_mov_b32_e32 v61, v8
	v_mov_b32_e32 v62, v8
	v_mov_b32_e32 v63, v8
	v_mov_b32_e32 v68, v8
	v_mov_b32_e32 v69, v8
	v_mov_b32_e32 v70, v8
	v_mov_b32_e32 v71, v8
	v_mov_b32_e32 v72, v8
	v_mov_b32_e32 v73, v8
	v_mov_b32_e32 v74, v8
	v_mov_b32_e32 v75, v8
	v_mov_b32_e32 v80, v8
	v_mov_b32_e32 v81, v8
	v_mov_b32_e32 v82, v8
	v_mov_b32_e32 v83, v8
	v_mov_b32_e32 v88, v8
	v_mov_b32_e32 v89, v8
	v_mov_b32_e32 v90, v8
	v_mov_b32_e32 v91, v8
	v_mov_b32_e32 v96, v8
	v_mov_b32_e32 v97, v8
	v_mov_b32_e32 v98, v8
	v_mov_b32_e32 v99, v8
	v_mov_b32_e32 v104, v8
	v_mov_b32_e32 v105, v8
	v_mov_b32_e32 v106, v8
	v_mov_b32_e32 v107, v8
	v_mov_b32_e32 v112, v8
	v_mov_b32_e32 v113, v8
	v_mov_b32_e32 v114, v8
	v_mov_b32_e32 v115, v8
	v_mov_b32_e32 v120, v8
	v_mov_b32_e32 v121, v8
	v_mov_b32_e32 v122, v8
	v_mov_b32_e32 v123, v8
	v_mov_b32_e32 v128, v8
	v_mov_b32_e32 v129, v8
	v_mov_b32_e32 v130, v8
	v_mov_b32_e32 v131, v8
	v_mov_b32_e32 v76, v8
	v_mov_b32_e32 v77, v8
	v_mov_b32_e32 v78, v8
	v_mov_b32_e32 v79, v8
	v_mov_b32_e32 v84, v8
	v_mov_b32_e32 v85, v8
	v_mov_b32_e32 v86, v8
	v_mov_b32_e32 v87, v8
	v_mov_b32_e32 v92, v8
	v_mov_b32_e32 v93, v8
	v_mov_b32_e32 v94, v8
	v_mov_b32_e32 v95, v8
	v_mov_b32_e32 v100, v8
	v_mov_b32_e32 v101, v8
	v_mov_b32_e32 v102, v8
	v_mov_b32_e32 v103, v8
	v_mov_b32_e32 v108, v8
	v_mov_b32_e32 v109, v8
	v_mov_b32_e32 v110, v8
	v_mov_b32_e32 v111, v8
	v_mov_b32_e32 v116, v8
	v_mov_b32_e32 v117, v8
	v_mov_b32_e32 v118, v8
	v_mov_b32_e32 v119, v8
	v_mov_b32_e32 v124, v8
	v_mov_b32_e32 v125, v8
	v_mov_b32_e32 v126, v8
	v_mov_b32_e32 v127, v8
	v_mov_b32_e32 v132, v8
	v_mov_b32_e32 v133, v8
	v_mov_b32_e32 v134, v8
	v_mov_b32_e32 v135, v8
	s_cmp_eq_u32 s101, 0
	s_cbranch_scc0 .Lsp_0
	s_setprio 1

; template <class Epi>
; __device__ __forceinline__ void gemm_phase(PG8_LAS unsigned char* lds, const Gemm g, const StaticOrder& S, const Epi& E) {
;     ...
;     f32x4 acc[2][2][4][2];
; #pragma unroll
;     for (int a = 0; a < 2; ++a)
; #pragma unroll
;         for (int b = 0; b < 2; ++b)
; #pragma unroll
;             for (int m = 0; m < 4; ++m)
; #pragma unroll
;                 for (int n = 0; n < 2; ++n) acc[a][b][m][n] = (f32x4){0.f, 0.f, 0.f, 0.f};
;     ...
;         for (int t = 0; t < nt; t += 2) {
;             const bool last = (t == nt - 2);
;             const char* a1 = cA + (size_t)(t + 1) * kstep;
;             const char* a2 = last ? nA : cA + (size_t)(t + 2) * kstep; const char* b2 = last ? nB : cB + (size_t)(t + 2) * kstep;
.LBB0_316:
	s_add_u32 s20, s12, 0x160080
	s_addc_u32 s21, s13, 0
	s_add_u32 s48, s10, 0x100
	v_mov_b32_e32 v0, 0
	s_addc_u32 s49, s11, 0
	s_mov_b32 s50, -2
	s_waitcnt lgkmcnt(0)
	v_mov_b32_e32 v1, v0
	v_mov_b32_e32 v2, v0
	v_mov_b32_e32 v3, v0
	v_mov_b32_e32 v4, v0
	v_mov_b32_e32 v5, v0
	v_mov_b32_e32 v6, v0
	v_mov_b32_e32 v7, v0
	v_mov_b32_e32 v16, v0
	v_mov_b32_e32 v17, v0
	v_mov_b32_e32 v18, v0
	v_mov_b32_e32 v19, v0
	v_mov_b32_e32 v20, v0
	v_mov_b32_e32 v21, v0
	v_mov_b32_e32 v22, v0
	v_mov_b32_e32 v23, v0
	v_mov_b32_e32 v32, v0
	v_mov_b32_e32 v33, v0
	v_mov_b32_e32 v34, v0
	v_mov_b32_e32 v35, v0
	v_mov_b32_e32 v36, v0
	v_mov_b32_e32 v37, v0
	v_mov_b32_e32 v38, v0
	v_mov_b32_e32 v39, v0
	v_mov_b32_e32 v48, v0
	v_mov_b32_e32 v49, v0
	v_mov_b32_e32 v50, v0
	v_mov_b32_e32 v51, v0
	v_mov_b32_e32 v52, v0
	v_mov_b32_e32 v53, v0
	v_mov_b32_e32 v54, v0
	v_mov_b32_e32 v55, v0
	v_mov_b32_e32 v12, v0
	v_mov_b32_e32 v13, v0
	v_mov_b32_e32 v14, v0
	v_mov_b32_e32 v15, v0
	v_mov_b32_e32 v8, v0
	v_mov_b32_e32 v9, v0
	v_mov_b32_e32 v10, v0
	v_mov_b32_e32 v11, v0
	v_mov_b32_e32 v28, v0
	v_mov_b32_e32 v29, v0
	v_mov_b32_e32 v30, v0
	v_mov_b32_e32 v31, v0
	v_mov_b32_e32 v24, v0
	v_mov_b32_e32 v25, v0
	v_mov_b32_e32 v26, v0
	v_mov_b32_e32 v27, v0
	v_mov_b32_e32 v44, v0
	v_mov_b32_e32 v45, v0
	v_mov_b32_e32 v46, v0
	v_mov_b32_e32 v47, v0
	v_mov_b32_e32 v40, v0
	v_mov_b32_e32 v41, v0
	v_mov_b32_e32 v42, v0
	v_mov_b32_e32 v43, v0
	v_mov_b32_e32 v56, v0
	v_mov_b32_e32 v57, v0
	v_mov_b32_e32 v58, v0
	v_mov_b32_e32 v59, v0
	v_mov_b32_e32 v60, v0
	v_mov_b32_e32 v61, v0
	v_mov_b32_e32 v62, v0
	v_mov_b32_e32 v63, v0
	v_mov_b32_e32 v64, v0
	v_mov_b32_e32 v65, v0
	v_mov_b32_e32 v66, v0
	v_mov_b32_e32 v67, v0
	v_mov_b32_e32 v68, v0
	v_mov_b32_e32 v69, v0
	v_mov_b32_e32 v70, v0
	v_mov_b32_e32 v71, v0
	v_mov_b32_e32 v80, v0
	v_mov_b32_e32 v81, v0
	v_mov_b32_e32 v82, v0
	v_mov_b32_e32 v83, v0
	v_mov_b32_e32 v84, v0
	v_mov_b32_e32 v85, v0
	v_mov_b32_e32 v86, v0
	v_mov_b32_e32 v87, v0
	v_mov_b32_e32 v96, v0
	v_mov_b32_e32 v97, v0
	v_mov_b32_e32 v98, v0
	v_mov_b32_e32 v99, v0
	v_mov_b32_e32 v100, v0
	v_mov_b32_e32 v101, v0
	v_mov_b32_e32 v102, v0
	v_mov_b32_e32 v103, v0
	v_mov_b32_e32 v112, v0
	v_mov_b32_e32 v113, v0
	v_mov_b32_e32 v114, v0
	v_mov_b32_e32 v115, v0
	v_mov_b32_e32 v116, v0
	v_mov_b32_e32 v117, v0
	v_mov_b32_e32 v118, v0
	v_mov_b32_e32 v119, v0
	v_mov_b32_e32 v76, v0
	v_mov_b32_e32 v77, v0
	v_mov_b32_e32 v78, v0
	v_mov_b32_e32 v79, v0
	v_mov_b32_e32 v72, v0
	v_mov_b32_e32 v73, v0
	v_mov_b32_e32 v74, v0
	v_mov_b32_e32 v75, v0
	v_mov_b32_e32 v92, v0
	v_mov_b32_e32 v93, v0
	v_mov_b32_e32 v94, v0
	v_mov_b32_e32 v95, v0
	v_mov_b32_e32 v88, v0
	v_mov_b32_e32 v89, v0
	v_mov_b32_e32 v90, v0
	v_mov_b32_e32 v91, v0
	v_mov_b32_e32 v108, v0
	v_mov_b32_e32 v109, v0
	v_mov_b32_e32 v110, v0
	v_mov_b32_e32 v111, v0
	v_mov_b32_e32 v104, v0
	v_mov_b32_e32 v105, v0
	v_mov_b32_e32 v106, v0
	v_mov_b32_e32 v107, v0
	v_mov_b32_e32 v120, v0
	v_mov_b32_e32 v121, v0
	v_mov_b32_e32 v122, v0
	v_mov_b32_e32 v123, v0
	v_mov_b32_e32 v124, v0
	v_mov_b32_e32 v125, v0
	v_mov_b32_e32 v126, v0
	v_mov_b32_e32 v127, v0
	s_cmp_eq_u32 s101, 0
	s_cbranch_scc0 .Lsp_1
	s_setprio 1

; #define PG8_STAGE(bufoff, gbase, voff) do { _Pragma("unroll") for (int _i = 0; _i < 2; ++_i) \
;         __builtin_amdgcn_global_load_lds((const unsigned*)((const char*)(gbase) + (voff)[_i]), (PG8_LAS unsigned*)(lds + (bufoff) + ldsw + _i * 8192), 16, 0, 0); } while (0)
; #define PG8_WAIT_V(n) asm volatile("s_waitcnt vmcnt(" #n ")" ::: "memory")
; #define PG8_BAR __builtin_amdgcn_s_barrier()
; template <class Epi>
; __device__ __forceinline__ void gemm_phase(PG8_LAS unsigned char* lds, const Gemm g, const StaticOrder& S, const Epi& E) {
;     ...
;     f32x4 acc[2][2][4][2];
; #pragma unroll
;     for (int a = 0; a < 2; ++a)
; #pragma unroll
;         for (int b = 0; b < 2; ++b)
; #pragma unroll
;             for (int m = 0; m < 4; ++m)
; #pragma unroll
;                 for (int n = 0; n < 2; ++n) acc[a][b][m][n] = (f32x4){0.f, 0.f, 0.f, 0.f};
;     bf16x8 At[4][2], B0[2][2], B1[2][2];
;     const char* cA = (const char*)g.A + (size_t)cur.pm * tstepA; const char* cB = (const char*)g.Bt + (size_t)cur.pn * tstepB;
;     PG8_STAGE(PG8_SB(0, 0), cB, voffB); PG8_STAGE(PG8_SA(0, 0), cA, voffA); PG8_STAGE(PG8_SB(0, 1), cB + hstepB, voffB); PG8_STAGE(PG8_SA(0, 1), cA + hstepA, voffA);
;     if (wr == 1) PG8_BAR;
;     PG8_WAIT_V(4); PG8_BAR;
;     PG8_STAGE(PG8_SB(1, 0), cB + kstep, voffB); PG8_STAGE(PG8_SA(1, 0), cA + kstep, voffA); PG8_STAGE(PG8_SB(1, 1), cB + hstepB + kstep, voffB);
;     PG8_WAIT_V(6); PG8_BAR;
;     for (;;) {
;         const bool has_next = S.next(ui + 1, nxt);
;         const char* nA = has_next ? (const char*)g.A + (size_t)nxt.pm * tstepA : cA; const char* nB = has_next ? (const char*)g.Bt + (size_t)nxt.pn * tstepB : cB;
;         for (int t = 0; t < nt; t += 2) {
;             const bool last = (t == nt - 2);
;             const char* a1 = cA + (size_t)(t + 1) * kstep;
;             const char* a2 = last ? nA : cA + (size_t)(t + 2) * kstep; const char* b2 = last ? nB : cB + (size_t)(t + 2) * kstep;
.LBB0_412:
	s_ashr_i32 s57, s56, 31
	v_cmp_lt_i64_e32 vcc, s[6:7], v[144:145]
	s_lshl_b64 s[6:7], s[56:57], 20
	s_add_u32 s58, s76, s6
	s_addc_u32 s59, s77, s7
	s_and_b64 s[6:7], vcc, exec
	s_cselect_b32 s53, s59, s1
	s_cselect_b32 s57, s58, s0
	s_ashr_i32 s55, s54, 31
	s_lshl_b64 s[6:7], s[54:55], 20
	v_readlane_b32 s48, v253, 34
	v_readlane_b32 s49, v253, 35
	s_add_u32 s60, s48, s6
	s_addc_u32 s61, s49, s7
	s_and_b64 s[6:7], vcc, exec
	s_cselect_b32 s55, s61, s5
	s_cselect_b32 s63, s60, s4
	s_add_u32 s0, s0, 0x80080
	s_addc_u32 s1, s1, 0
	s_add_u32 s65, s4, 0x100
	v_mov_b32_e32 v0, 0
	s_addc_u32 s66, s5, 0
	s_mov_b32 s67, -2
	v_mov_b32_e32 v1, v0
	v_mov_b32_e32 v2, v0
	v_mov_b32_e32 v3, v0
	v_mov_b32_e32 v4, v0
	v_mov_b32_e32 v5, v0
	v_mov_b32_e32 v6, v0
	v_mov_b32_e32 v7, v0
	v_mov_b32_e32 v16, v0
	v_mov_b32_e32 v17, v0
	v_mov_b32_e32 v18, v0
	v_mov_b32_e32 v19, v0
	v_mov_b32_e32 v20, v0
	v_mov_b32_e32 v21, v0
	v_mov_b32_e32 v22, v0
	v_mov_b32_e32 v23, v0
	v_mov_b32_e32 v32, v0
	v_mov_b32_e32 v33, v0
	v_mov_b32_e32 v34, v0
	v_mov_b32_e32 v35, v0
	v_mov_b32_e32 v36, v0
	v_mov_b32_e32 v37, v0
	v_mov_b32_e32 v38, v0
	v_mov_b32_e32 v39, v0
	v_mov_b32_e32 v48, v0
	v_mov_b32_e32 v49, v0
	v_mov_b32_e32 v50, v0
	v_mov_b32_e32 v51, v0
	v_mov_b32_e32 v52, v0
	v_mov_b32_e32 v53, v0
	v_mov_b32_e32 v54, v0
	v_mov_b32_e32 v55, v0
	v_mov_b32_e32 v8, v0
	v_mov_b32_e32 v9, v0
	v_mov_b32_e32 v10, v0
	v_mov_b32_e32 v11, v0
	v_mov_b32_e32 v12, v0
	v_mov_b32_e32 v13, v0
	v_mov_b32_e32 v14, v0
	v_mov_b32_e32 v15, v0
	v_mov_b32_e32 v24, v0
	v_mov_b32_e32 v25, v0
	v_mov_b32_e32 v26, v0
	v_mov_b32_e32 v27, v0
	v_mov_b32_e32 v28, v0
	v_mov_b32_e32 v29, v0
	v_mov_b32_e32 v30, v0
	v_mov_b32_e32 v31, v0
	v_mov_b32_e32 v40, v0
	v_mov_b32_e32 v41, v0
	v_mov_b32_e32 v42, v0
	v_mov_b32_e32 v43, v0
	v_mov_b32_e32 v44, v0
	v_mov_b32_e32 v45, v0
	v_mov_b32_e32 v46, v0
	v_mov_b32_e32 v47, v0
	v_mov_b32_e32 v56, v0
	v_mov_b32_e32 v57, v0
	v_mov_b32_e32 v58, v0
	v_mov_b32_e32 v59, v0
	v_mov_b32_e32 v60, v0
	v_mov_b32_e32 v61, v0
	v_mov_b32_e32 v62, v0
	v_mov_b32_e32 v63, v0
	v_mov_b32_e32 v64, v0
	v_mov_b32_e32 v65, v0
	v_mov_b32_e32 v66, v0
	v_mov_b32_e32 v67, v0
	v_mov_b32_e32 v68, v0
	v_mov_b32_e32 v69, v0
	v_mov_b32_e32 v70, v0
	v_mov_b32_e32 v71, v0
	v_mov_b32_e32 v80, v0
	v_mov_b32_e32 v81, v0
	v_mov_b32_e32 v82, v0
	v_mov_b32_e32 v83, v0
	v_mov_b32_e32 v84, v0
	v_mov_b32_e32 v85, v0
	v_mov_b32_e32 v86, v0
	v_mov_b32_e32 v87, v0
	v_mov_b32_e32 v96, v0
	v_mov_b32_e32 v97, v0
	v_mov_b32_e32 v98, v0
	v_mov_b32_e32 v99, v0
	v_mov_b32_e32 v100, v0
	v_mov_b32_e32 v101, v0
	v_mov_b32_e32 v102, v0
	v_mov_b32_e32 v103, v0
	v_mov_b32_e32 v112, v0
	v_mov_b32_e32 v113, v0
	v_mov_b32_e32 v114, v0
	v_mov_b32_e32 v115, v0
	v_mov_b32_e32 v116, v0
	v_mov_b32_e32 v117, v0
	v_mov_b32_e32 v118, v0
	v_mov_b32_e32 v119, v0
	v_mov_b32_e32 v72, v0
	v_mov_b32_e32 v73, v0
	v_mov_b32_e32 v74, v0
	v_mov_b32_e32 v75, v0
	v_mov_b32_e32 v76, v0
	v_mov_b32_e32 v77, v0
	v_mov_b32_e32 v78, v0
	v_mov_b32_e32 v79, v0
	v_mov_b32_e32 v88, v0
	v_mov_b32_e32 v89, v0
	v_mov_b32_e32 v90, v0
	v_mov_b32_e32 v91, v0
	v_mov_b32_e32 v92, v0
	v_mov_b32_e32 v93, v0
	v_mov_b32_e32 v94, v0
	v_mov_b32_e32 v95, v0
	v_mov_b32_e32 v104, v0
	v_mov_b32_e32 v105, v0
	v_mov_b32_e32 v106, v0
	v_mov_b32_e32 v107, v0
	v_mov_b32_e32 v108, v0
	v_mov_b32_e32 v109, v0
	v_mov_b32_e32 v110, v0
	v_mov_b32_e32 v111, v0
	v_mov_b32_e32 v120, v0
	v_mov_b32_e32 v121, v0
	v_mov_b32_e32 v122, v0
	v_mov_b32_e32 v123, v0
	v_mov_b32_e32 v124, v0
	v_mov_b32_e32 v125, v0
	v_mov_b32_e32 v126, v0
	v_mov_b32_e32 v127, v0
	s_cmp_eq_u32 s101, 0
	s_cbranch_scc0 .Lsp_2
	s_setprio 1

; #define PG8_STAGE(bufoff, gbase, voff) do { _Pragma("unroll") for (int _i = 0; _i < 2; ++_i) \
;         __builtin_amdgcn_global_load_lds((const unsigned*)((const char*)(gbase) + (voff)[_i]), (PG8_LAS unsigned*)(lds + (bufoff) + ldsw + _i * 8192), 16, 0, 0); } while (0)
; #define PG8_WAIT_V(n) asm volatile("s_waitcnt vmcnt(" #n ")" ::: "memory")
; #define PG8_BAR __builtin_amdgcn_s_barrier()
; template <class Epi>
; __device__ __forceinline__ void gemm_phase(PG8_LAS unsigned char* lds, const Gemm g, const StaticOrder& S, const Epi& E) {
;     ...
;     f32x4 acc[2][2][4][2];
; #pragma unroll
;     for (int a = 0; a < 2; ++a)
; #pragma unroll
;         for (int b = 0; b < 2; ++b)
; #pragma unroll
;             for (int m = 0; m < 4; ++m)
; #pragma unroll
;                 for (int n = 0; n < 2; ++n) acc[a][b][m][n] = (f32x4){0.f, 0.f, 0.f, 0.f};
;     bf16x8 At[4][2], B0[2][2], B1[2][2];
;     const char* cA = (const char*)g.A + (size_t)cur.pm * tstepA; const char* cB = (const char*)g.Bt + (size_t)cur.pn * tstepB;
;     PG8_STAGE(PG8_SB(0, 0), cB, voffB); PG8_STAGE(PG8_SA(0, 0), cA, voffA); PG8_STAGE(PG8_SB(0, 1), cB + hstepB, voffB); PG8_STAGE(PG8_SA(0, 1), cA + hstepA, voffA);
;     if (wr == 1) PG8_BAR;
;     PG8_WAIT_V(4); PG8_BAR;
;     PG8_STAGE(PG8_SB(1, 0), cB + kstep, voffB); PG8_STAGE(PG8_SA(1, 0), cA + kstep, voffA); PG8_STAGE(PG8_SB(1, 1), cB + hstepB + kstep, voffB);
;     PG8_WAIT_V(6); PG8_BAR;
;     for (;;) {
;         const bool has_next = S.next(ui + 1, nxt);
;         const char* nA = has_next ? (const char*)g.A + (size_t)nxt.pm * tstepA : cA; const char* nB = has_next ? (const char*)g.Bt + (size_t)nxt.pn * tstepB : cB;
;         for (int t = 0; t < nt; t += 2) {
;             const bool last = (t == nt - 2);
;             const char* a1 = cA + (size_t)(t + 1) * kstep;
;             const char* a2 = last ? nA : cA + (size_t)(t + 2) * kstep; const char* b2 = last ? nB : cB + (size_t)(t + 2) * kstep;
.LBB0_903:
	s_ashr_i32 s15, s14, 31
	v_cmp_lt_i64_e32 vcc, s[16:17], v[160:161]
	s_lshl_b64 s[16:17], s[14:15], 19
	s_add_u32 s16, s80, s16
	s_addc_u32 s17, s81, s17
	s_and_b64 s[18:19], vcc, exec
	s_cselect_b32 s15, s17, s29
	s_cselect_b32 s54, s16, s28
	s_ashr_i32 s13, s12, 31
	s_lshl_b64 s[18:19], s[12:13], 19
	s_add_u32 s18, s64, s18
	s_addc_u32 s19, s65, s19
	s_and_b64 s[30:31], vcc, exec
	s_cselect_b32 s13, s19, s23
	s_cselect_b32 s55, s18, s22
	s_add_u32 s28, s28, 0x40080
	s_addc_u32 s29, s29, 0
	s_add_u32 s56, s22, 0x100
	v_mov_b32_e32 v0, 0
	s_addc_u32 s57, s23, 0
	s_mov_b32 s58, -2
	v_mov_b32_e32 v1, v0
	v_mov_b32_e32 v2, v0
	v_mov_b32_e32 v3, v0
	v_mov_b32_e32 v4, v0
	v_mov_b32_e32 v5, v0
	v_mov_b32_e32 v6, v0
	v_mov_b32_e32 v7, v0
	v_mov_b32_e32 v16, v0
	v_mov_b32_e32 v17, v0
	v_mov_b32_e32 v18, v0
	v_mov_b32_e32 v19, v0
	v_mov_b32_e32 v20, v0
	v_mov_b32_e32 v21, v0
	v_mov_b32_e32 v22, v0
	v_mov_b32_e32 v23, v0
	v_mov_b32_e32 v32, v0
	v_mov_b32_e32 v33, v0
	v_mov_b32_e32 v34, v0
	v_mov_b32_e32 v35, v0
	v_mov_b32_e32 v36, v0
	v_mov_b32_e32 v37, v0
	v_mov_b32_e32 v38, v0
	v_mov_b32_e32 v39, v0
	v_mov_b32_e32 v48, v0
	v_mov_b32_e32 v49, v0
	v_mov_b32_e32 v50, v0
	v_mov_b32_e32 v51, v0
	v_mov_b32_e32 v52, v0
	v_mov_b32_e32 v53, v0
	v_mov_b32_e32 v54, v0
	v_mov_b32_e32 v55, v0
	v_mov_b32_e32 v8, v0
	v_mov_b32_e32 v9, v0
	v_mov_b32_e32 v10, v0
	v_mov_b32_e32 v11, v0
	v_mov_b32_e32 v12, v0
	v_mov_b32_e32 v13, v0
	v_mov_b32_e32 v14, v0
	v_mov_b32_e32 v15, v0
	v_mov_b32_e32 v24, v0
	v_mov_b32_e32 v25, v0
	v_mov_b32_e32 v26, v0
	v_mov_b32_e32 v27, v0
	v_mov_b32_e32 v28, v0
	v_mov_b32_e32 v29, v0
	v_mov_b32_e32 v30, v0
	v_mov_b32_e32 v31, v0
	v_mov_b32_e32 v40, v0
	v_mov_b32_e32 v41, v0
	v_mov_b32_e32 v42, v0
	v_mov_b32_e32 v43, v0
	v_mov_b32_e32 v44, v0
	v_mov_b32_e32 v45, v0
	v_mov_b32_e32 v46, v0
	v_mov_b32_e32 v47, v0
	v_mov_b32_e32 v56, v0
	v_mov_b32_e32 v57, v0
	v_mov_b32_e32 v58, v0
	v_mov_b32_e32 v59, v0
	v_mov_b32_e32 v60, v0
	v_mov_b32_e32 v61, v0
	v_mov_b32_e32 v62, v0
	v_mov_b32_e32 v63, v0
	v_mov_b32_e32 v64, v0
	v_mov_b32_e32 v65, v0
	v_mov_b32_e32 v66, v0
	v_mov_b32_e32 v67, v0
	v_mov_b32_e32 v68, v0
	v_mov_b32_e32 v69, v0
	v_mov_b32_e32 v70, v0
	v_mov_b32_e32 v71, v0
	v_mov_b32_e32 v80, v0
	v_mov_b32_e32 v81, v0
	v_mov_b32_e32 v82, v0
	v_mov_b32_e32 v83, v0
	v_mov_b32_e32 v84, v0
	v_mov_b32_e32 v85, v0
	v_mov_b32_e32 v86, v0
	v_mov_b32_e32 v87, v0
	v_mov_b32_e32 v96, v0
	v_mov_b32_e32 v97, v0
	v_mov_b32_e32 v98, v0
	v_mov_b32_e32 v99, v0
	v_mov_b32_e32 v100, v0
	v_mov_b32_e32 v101, v0
	v_mov_b32_e32 v102, v0
	v_mov_b32_e32 v103, v0
	v_mov_b32_e32 v112, v0
	v_mov_b32_e32 v113, v0
	v_mov_b32_e32 v114, v0
	v_mov_b32_e32 v115, v0
	v_mov_b32_e32 v116, v0
	v_mov_b32_e32 v117, v0
	v_mov_b32_e32 v118, v0
	v_mov_b32_e32 v119, v0
	v_mov_b32_e32 v72, v0
	v_mov_b32_e32 v73, v0
	v_mov_b32_e32 v74, v0
	v_mov_b32_e32 v75, v0
	v_mov_b32_e32 v76, v0
	v_mov_b32_e32 v77, v0
	v_mov_b32_e32 v78, v0
	v_mov_b32_e32 v79, v0
	v_mov_b32_e32 v88, v0
	v_mov_b32_e32 v89, v0
	v_mov_b32_e32 v90, v0
	v_mov_b32_e32 v91, v0
	v_mov_b32_e32 v92, v0
	v_mov_b32_e32 v93, v0
	v_mov_b32_e32 v94, v0
	v_mov_b32_e32 v95, v0
	v_mov_b32_e32 v104, v0
	v_mov_b32_e32 v105, v0
	v_mov_b32_e32 v106, v0
	v_mov_b32_e32 v107, v0
	v_mov_b32_e32 v108, v0
	v_mov_b32_e32 v109, v0
	v_mov_b32_e32 v110, v0
	v_mov_b32_e32 v111, v0
	v_mov_b32_e32 v120, v0
	v_mov_b32_e32 v121, v0
	v_mov_b32_e32 v122, v0
	v_mov_b32_e32 v123, v0
	v_mov_b32_e32 v124, v0
	v_mov_b32_e32 v125, v0
	v_mov_b32_e32 v126, v0
	v_mov_b32_e32 v127, v0
	s_cmp_eq_u32 s101, 0
	s_cbranch_scc0 .Lsp_3
	s_setprio 1

; #define PG8_STAGE(bufoff, gbase, voff) do { _Pragma("unroll") for (int _i = 0; _i < 2; ++_i) \
;         __builtin_amdgcn_global_load_lds((const unsigned*)((const char*)(gbase) + (voff)[_i]), (PG8_LAS unsigned*)(lds + (bufoff) + ldsw + _i * 8192), 16, 0, 0); } while (0)
; #define PG8_WAIT_V(n) asm volatile("s_waitcnt vmcnt(" #n ")" ::: "memory")
; #define PG8_BAR __builtin_amdgcn_s_barrier()
; template <class Epi>
; __device__ __forceinline__ void gemm_phase(PG8_LAS unsigned char* lds, const Gemm g, const StaticOrder& S, const Epi& E) {
;     ...
;     f32x4 acc[2][2][4][2];
; #pragma unroll
;     for (int a = 0; a < 2; ++a)
; #pragma unroll
;         for (int b = 0; b < 2; ++b)
; #pragma unroll
;             for (int m = 0; m < 4; ++m)
; #pragma unroll
;                 for (int n = 0; n < 2; ++n) acc[a][b][m][n] = (f32x4){0.f, 0.f, 0.f, 0.f};
;     bf16x8 At[4][2], B0[2][2], B1[2][2];
;     const char* cA = (const char*)g.A + (size_t)cur.pm * tstepA; const char* cB = (const char*)g.Bt + (size_t)cur.pn * tstepB;
;     PG8_STAGE(PG8_SB(0, 0), cB, voffB); PG8_STAGE(PG8_SA(0, 0), cA, voffA); PG8_STAGE(PG8_SB(0, 1), cB + hstepB, voffB); PG8_STAGE(PG8_SA(0, 1), cA + hstepA, voffA);
;     if (wr == 1) PG8_BAR;
;     PG8_WAIT_V(4); PG8_BAR;
;     PG8_STAGE(PG8_SB(1, 0), cB + kstep, voffB); PG8_STAGE(PG8_SA(1, 0), cA + kstep, voffA); PG8_STAGE(PG8_SB(1, 1), cB + hstepB + kstep, voffB);
;     PG8_WAIT_V(6); PG8_BAR;
;     for (;;) {
;         const bool has_next = S.next(ui + 1, nxt);
;         const char* nA = has_next ? (const char*)g.A + (size_t)nxt.pm * tstepA : cA; const char* nB = has_next ? (const char*)g.Bt + (size_t)nxt.pn * tstepB : cB;
;         for (int t = 0; t < nt; t += 2) {
;             const bool last = (t == nt - 2);
;             const char* a1 = cA + (size_t)(t + 1) * kstep;
;             const char* a2 = last ? nA : cA + (size_t)(t + 2) * kstep; const char* b2 = last ? nB : cB + (size_t)(t + 2) * kstep;
.LBB0_924:
	s_ashr_i32 s17, s16, 31
	v_cmp_lt_i64_e32 vcc, s[18:19], v[182:183]
	s_lshl_b64 s[18:19], s[16:17], 19
	s_add_u32 s18, s90, s18
	s_addc_u32 s19, s91, s19
	s_and_b64 s[20:21], vcc, exec
	s_cselect_b32 s17, s19, s31
	s_cselect_b32 s57, s18, s30
	s_ashr_i32 s15, s14, 31
	s_lshl_b64 s[20:21], s[14:15], 19
	v_readlane_b32 s34, v253, 38
	v_readlane_b32 s35, v253, 39
	s_add_u32 s20, s34, s20
	s_addc_u32 s21, s35, s21
	s_and_b64 s[34:35], vcc, exec
	s_cselect_b32 s15, s21, s23
	s_cselect_b32 s58, s20, s22
	s_add_u32 s30, s30, 0x40080
	s_addc_u32 s31, s31, 0
	s_add_u32 s59, s22, 0x100
	v_mov_b32_e32 v0, 0
	s_addc_u32 s60, s23, 0
	s_mov_b32 s61, -2
	v_mov_b32_e32 v1, v0
	v_mov_b32_e32 v2, v0
	v_mov_b32_e32 v3, v0
	v_mov_b32_e32 v4, v0
	v_mov_b32_e32 v5, v0
	v_mov_b32_e32 v6, v0
	v_mov_b32_e32 v7, v0
	v_mov_b32_e32 v16, v0
	v_mov_b32_e32 v17, v0
	v_mov_b32_e32 v18, v0
	v_mov_b32_e32 v19, v0
	v_mov_b32_e32 v20, v0
	v_mov_b32_e32 v21, v0
	v_mov_b32_e32 v22, v0
	v_mov_b32_e32 v23, v0
	v_mov_b32_e32 v32, v0
	v_mov_b32_e32 v33, v0
	v_mov_b32_e32 v34, v0
	v_mov_b32_e32 v35, v0
	v_mov_b32_e32 v36, v0
	v_mov_b32_e32 v37, v0
	v_mov_b32_e32 v38, v0
	v_mov_b32_e32 v39, v0
	v_mov_b32_e32 v48, v0
	v_mov_b32_e32 v49, v0
	v_mov_b32_e32 v50, v0
	v_mov_b32_e32 v51, v0
	v_mov_b32_e32 v52, v0
	v_mov_b32_e32 v53, v0
	v_mov_b32_e32 v54, v0
	v_mov_b32_e32 v55, v0
	v_mov_b32_e32 v8, v0
	v_mov_b32_e32 v9, v0
	v_mov_b32_e32 v10, v0
	v_mov_b32_e32 v11, v0
	v_mov_b32_e32 v12, v0
	v_mov_b32_e32 v13, v0
	v_mov_b32_e32 v14, v0
	v_mov_b32_e32 v15, v0
	v_mov_b32_e32 v24, v0
	v_mov_b32_e32 v25, v0
	v_mov_b32_e32 v26, v0
	v_mov_b32_e32 v27, v0
	v_mov_b32_e32 v28, v0
	v_mov_b32_e32 v29, v0
	v_mov_b32_e32 v30, v0
	v_mov_b32_e32 v31, v0
	v_mov_b32_e32 v40, v0
	v_mov_b32_e32 v41, v0
	v_mov_b32_e32 v42, v0
	v_mov_b32_e32 v43, v0
	v_mov_b32_e32 v44, v0
	v_mov_b32_e32 v45, v0
	v_mov_b32_e32 v46, v0
	v_mov_b32_e32 v47, v0
	v_mov_b32_e32 v56, v0
	v_mov_b32_e32 v57, v0
	v_mov_b32_e32 v58, v0
	v_mov_b32_e32 v59, v0
	v_mov_b32_e32 v60, v0
	v_mov_b32_e32 v61, v0
	v_mov_b32_e32 v62, v0
	v_mov_b32_e32 v63, v0
	v_mov_b32_e32 v64, v0
	v_mov_b32_e32 v65, v0
	v_mov_b32_e32 v66, v0
	v_mov_b32_e32 v67, v0
	v_mov_b32_e32 v68, v0
	v_mov_b32_e32 v69, v0
	v_mov_b32_e32 v70, v0
	v_mov_b32_e32 v71, v0
	v_mov_b32_e32 v80, v0
	v_mov_b32_e32 v81, v0
	v_mov_b32_e32 v82, v0
	v_mov_b32_e32 v83, v0
	v_mov_b32_e32 v84, v0
	v_mov_b32_e32 v85, v0
	v_mov_b32_e32 v86, v0
	v_mov_b32_e32 v87, v0
	v_mov_b32_e32 v96, v0
	v_mov_b32_e32 v97, v0
	v_mov_b32_e32 v98, v0
	v_mov_b32_e32 v99, v0
	v_mov_b32_e32 v100, v0
	v_mov_b32_e32 v101, v0
	v_mov_b32_e32 v102, v0
	v_mov_b32_e32 v103, v0
	v_mov_b32_e32 v112, v0
	v_mov_b32_e32 v113, v0
	v_mov_b32_e32 v114, v0
	v_mov_b32_e32 v115, v0
	v_mov_b32_e32 v116, v0
	v_mov_b32_e32 v117, v0
	v_mov_b32_e32 v118, v0
	v_mov_b32_e32 v119, v0
	v_mov_b32_e32 v72, v0
	v_mov_b32_e32 v73, v0
	v_mov_b32_e32 v74, v0
	v_mov_b32_e32 v75, v0
	v_mov_b32_e32 v76, v0
	v_mov_b32_e32 v77, v0
	v_mov_b32_e32 v78, v0
	v_mov_b32_e32 v79, v0
	v_mov_b32_e32 v88, v0
	v_mov_b32_e32 v89, v0
	v_mov_b32_e32 v90, v0
	v_mov_b32_e32 v91, v0
	v_mov_b32_e32 v92, v0
	v_mov_b32_e32 v93, v0
	v_mov_b32_e32 v94, v0
	v_mov_b32_e32 v95, v0
	v_mov_b32_e32 v104, v0
	v_mov_b32_e32 v105, v0
	v_mov_b32_e32 v106, v0
	v_mov_b32_e32 v107, v0
	v_mov_b32_e32 v108, v0
	v_mov_b32_e32 v109, v0
	v_mov_b32_e32 v110, v0
	v_mov_b32_e32 v111, v0
	v_mov_b32_e32 v120, v0
	v_mov_b32_e32 v121, v0
	v_mov_b32_e32 v122, v0
	v_mov_b32_e32 v123, v0
	v_mov_b32_e32 v124, v0
	v_mov_b32_e32 v125, v0
	v_mov_b32_e32 v126, v0
	v_mov_b32_e32 v127, v0
	s_waitcnt vmcnt(0)
	s_cmp_eq_u32 s101, 0
	s_cbranch_scc0 .Lsp_4
	s_setprio 1

; #define PG8_STAGE(bufoff, gbase, voff) do { _Pragma("unroll") for (int _i = 0; _i < 2; ++_i) \
;         __builtin_amdgcn_global_load_lds((const unsigned*)((const char*)(gbase) + (voff)[_i]), (PG8_LAS unsigned*)(lds + (bufoff) + ldsw + _i * 8192), 16, 0, 0); } while (0)
; #define PG8_WAIT_V(n) asm volatile("s_waitcnt vmcnt(" #n ")" ::: "memory")
; #define PG8_BAR __builtin_amdgcn_s_barrier()
; template <class Epi>
; __device__ __forceinline__ void gemm_phase(PG8_LAS unsigned char* lds, const Gemm g, const StaticOrder& S, const Epi& E) {
;     ...
;     f32x4 acc[2][2][4][2];
; #pragma unroll
;     for (int a = 0; a < 2; ++a)
; #pragma unroll
;         for (int b = 0; b < 2; ++b)
; #pragma unroll
;             for (int m = 0; m < 4; ++m)
; #pragma unroll
;                 for (int n = 0; n < 2; ++n) acc[a][b][m][n] = (f32x4){0.f, 0.f, 0.f, 0.f};
;     bf16x8 At[4][2], B0[2][2], B1[2][2];
;     const char* cA = (const char*)g.A + (size_t)cur.pm * tstepA; const char* cB = (const char*)g.Bt + (size_t)cur.pn * tstepB;
;     PG8_STAGE(PG8_SB(0, 0), cB, voffB); PG8_STAGE(PG8_SA(0, 0), cA, voffA); PG8_STAGE(PG8_SB(0, 1), cB + hstepB, voffB); PG8_STAGE(PG8_SA(0, 1), cA + hstepA, voffA);
;     if (wr == 1) PG8_BAR;
;     PG8_WAIT_V(4); PG8_BAR;
;     PG8_STAGE(PG8_SB(1, 0), cB + kstep, voffB); PG8_STAGE(PG8_SA(1, 0), cA + kstep, voffA); PG8_STAGE(PG8_SB(1, 1), cB + hstepB + kstep, voffB);
;     PG8_WAIT_V(6); PG8_BAR;
;     for (;;) {
;         const bool has_next = S.next(ui + 1, nxt);
;         const char* nA = has_next ? (const char*)g.A + (size_t)nxt.pm * tstepA : cA; const char* nB = has_next ? (const char*)g.Bt + (size_t)nxt.pn * tstepB : cB;
;         for (int t = 0; t < nt; t += 2) {
;             const bool last = (t == nt - 2);
;             const char* a1 = cA + (size_t)(t + 1) * kstep;
;             const char* a2 = last ? nA : cA + (size_t)(t + 2) * kstep; const char* b2 = last ? nB : cB + (size_t)(t + 2) * kstep;
.LBB0_1002:
	s_ashr_i32 s15, s14, 31
	v_cmp_lt_i64_e32 vcc, s[16:17], v[164:165]
	s_lshl_b64 s[16:17], s[14:15], 21
	s_add_u32 s16, s46, s16
	s_addc_u32 s17, s47, s17
	s_and_b64 s[18:19], vcc, exec
	s_cselect_b32 s15, s17, s29
	s_cselect_b32 s21, s16, s28
	s_ashr_i32 s13, s12, 31
	s_lshl_b64 s[18:19], s[12:13], 20
	v_readlane_b32 s30, v253, 40
	v_readlane_b32 s31, v253, 41
	s_add_u32 s18, s30, s18
	s_addc_u32 s19, s31, s19
	s_and_b64 s[30:31], vcc, exec
	s_cselect_b32 s13, s19, s23
	s_cselect_b32 s53, s18, s22
	s_add_u32 s28, s28, 0x100080
	s_addc_u32 s29, s29, 0
	s_add_u32 s54, s22, 0x100
	v_mov_b32_e32 v0, 0
	s_addc_u32 s55, s23, 0
	s_mov_b32 s56, -2
	s_waitcnt lgkmcnt(0)
	v_mov_b32_e32 v1, v0
	v_mov_b32_e32 v2, v0
	v_mov_b32_e32 v3, v0
	v_mov_b32_e32 v4, v0
	v_mov_b32_e32 v5, v0
	v_mov_b32_e32 v6, v0
	v_mov_b32_e32 v7, v0
	v_mov_b32_e32 v16, v0
	v_mov_b32_e32 v17, v0
	v_mov_b32_e32 v18, v0
	v_mov_b32_e32 v19, v0
	v_mov_b32_e32 v20, v0
	v_mov_b32_e32 v21, v0
	v_mov_b32_e32 v22, v0
	v_mov_b32_e32 v23, v0
	v_mov_b32_e32 v32, v0
	v_mov_b32_e32 v33, v0
	v_mov_b32_e32 v34, v0
	v_mov_b32_e32 v35, v0
	v_mov_b32_e32 v36, v0
	v_mov_b32_e32 v37, v0
	v_mov_b32_e32 v38, v0
	v_mov_b32_e32 v39, v0
	v_mov_b32_e32 v48, v0
	v_mov_b32_e32 v49, v0
	v_mov_b32_e32 v50, v0
	v_mov_b32_e32 v51, v0
	v_mov_b32_e32 v52, v0
	v_mov_b32_e32 v53, v0
	v_mov_b32_e32 v54, v0
	v_mov_b32_e32 v55, v0
	v_mov_b32_e32 v12, v0
	v_mov_b32_e32 v13, v0
	v_mov_b32_e32 v14, v0
	v_mov_b32_e32 v15, v0
	v_mov_b32_e32 v8, v0
	v_mov_b32_e32 v9, v0
	v_mov_b32_e32 v10, v0
	v_mov_b32_e32 v11, v0
	v_mov_b32_e32 v28, v0
	v_mov_b32_e32 v29, v0
	v_mov_b32_e32 v30, v0
	v_mov_b32_e32 v31, v0
	v_mov_b32_e32 v24, v0
	v_mov_b32_e32 v25, v0
	v_mov_b32_e32 v26, v0
	v_mov_b32_e32 v27, v0
	v_mov_b32_e32 v44, v0
	v_mov_b32_e32 v45, v0
	v_mov_b32_e32 v46, v0
	v_mov_b32_e32 v47, v0
	v_mov_b32_e32 v40, v0
	v_mov_b32_e32 v41, v0
	v_mov_b32_e32 v42, v0
	v_mov_b32_e32 v43, v0
	v_mov_b32_e32 v56, v0
	v_mov_b32_e32 v57, v0
	v_mov_b32_e32 v58, v0
	v_mov_b32_e32 v59, v0
	v_mov_b32_e32 v60, v0
	v_mov_b32_e32 v61, v0
	v_mov_b32_e32 v62, v0
	v_mov_b32_e32 v63, v0
	v_mov_b32_e32 v64, v0
	v_mov_b32_e32 v65, v0
	v_mov_b32_e32 v66, v0
	v_mov_b32_e32 v67, v0
	v_mov_b32_e32 v68, v0
	v_mov_b32_e32 v69, v0
	v_mov_b32_e32 v70, v0
	v_mov_b32_e32 v71, v0
	v_mov_b32_e32 v80, v0
	v_mov_b32_e32 v81, v0
	v_mov_b32_e32 v82, v0
	v_mov_b32_e32 v83, v0
	v_mov_b32_e32 v84, v0
	v_mov_b32_e32 v85, v0
	v_mov_b32_e32 v86, v0
	v_mov_b32_e32 v87, v0
	v_mov_b32_e32 v96, v0
	v_mov_b32_e32 v97, v0
	v_mov_b32_e32 v98, v0
	v_mov_b32_e32 v99, v0
	v_mov_b32_e32 v100, v0
	v_mov_b32_e32 v101, v0
	v_mov_b32_e32 v102, v0
	v_mov_b32_e32 v103, v0
	v_mov_b32_e32 v112, v0
	v_mov_b32_e32 v113, v0
	v_mov_b32_e32 v114, v0
	v_mov_b32_e32 v115, v0
	v_mov_b32_e32 v116, v0
	v_mov_b32_e32 v117, v0
	v_mov_b32_e32 v118, v0
	v_mov_b32_e32 v119, v0
	v_mov_b32_e32 v76, v0
	v_mov_b32_e32 v77, v0
	v_mov_b32_e32 v78, v0
	v_mov_b32_e32 v79, v0
	v_mov_b32_e32 v72, v0
	v_mov_b32_e32 v73, v0
	v_mov_b32_e32 v74, v0
	v_mov_b32_e32 v75, v0
	v_mov_b32_e32 v92, v0
	v_mov_b32_e32 v93, v0
	v_mov_b32_e32 v94, v0
	v_mov_b32_e32 v95, v0
	v_mov_b32_e32 v88, v0
	v_mov_b32_e32 v89, v0
	v_mov_b32_e32 v90, v0
	v_mov_b32_e32 v91, v0
	v_mov_b32_e32 v108, v0
	v_mov_b32_e32 v109, v0
	v_mov_b32_e32 v110, v0
	v_mov_b32_e32 v111, v0
	v_mov_b32_e32 v104, v0
	v_mov_b32_e32 v105, v0
	v_mov_b32_e32 v106, v0
	v_mov_b32_e32 v107, v0
	v_mov_b32_e32 v120, v0
	v_mov_b32_e32 v121, v0
	v_mov_b32_e32 v122, v0
	v_mov_b32_e32 v123, v0
	v_mov_b32_e32 v124, v0
	v_mov_b32_e32 v125, v0
	v_mov_b32_e32 v126, v0
	v_mov_b32_e32 v127, v0
	s_cmp_eq_u32 s101, 0
	s_cbranch_scc0 .Lsp_5
	s_setprio 1

; #define PG8_STAGE(bufoff, gbase, voff) do { _Pragma("unroll") for (int _i = 0; _i < 2; ++_i) \
;         __builtin_amdgcn_global_load_lds((const unsigned*)((const char*)(gbase) + (voff)[_i]), (PG8_LAS unsigned*)(lds + (bufoff) + ldsw + _i * 8192), 16, 0, 0); } while (0)
; #define PG8_WAIT_V(n) asm volatile("s_waitcnt vmcnt(" #n ")" ::: "memory")
; #define PG8_BAR __builtin_amdgcn_s_barrier()
; template <class Epi>
; __device__ __forceinline__ void gemm_phase(PG8_LAS unsigned char* lds, const Gemm g, const StaticOrder& S, const Epi& E) {
;     ...
;     f32x4 acc[2][2][4][2];
; #pragma unroll
;     for (int a = 0; a < 2; ++a)
; #pragma unroll
;         for (int b = 0; b < 2; ++b)
; #pragma unroll
;             for (int m = 0; m < 4; ++m)
; #pragma unroll
;                 for (int n = 0; n < 2; ++n) acc[a][b][m][n] = (f32x4){0.f, 0.f, 0.f, 0.f};
;     bf16x8 At[4][2], B0[2][2], B1[2][2];
;     const char* cA = (const char*)g.A + (size_t)cur.pm * tstepA; const char* cB = (const char*)g.Bt + (size_t)cur.pn * tstepB;
;     PG8_STAGE(PG8_SB(0, 0), cB, voffB); PG8_STAGE(PG8_SA(0, 0), cA, voffA); PG8_STAGE(PG8_SB(0, 1), cB + hstepB, voffB); PG8_STAGE(PG8_SA(0, 1), cA + hstepA, voffA);
;     if (wr == 1) PG8_BAR;
;     PG8_WAIT_V(4); PG8_BAR;
;     PG8_STAGE(PG8_SB(1, 0), cB + kstep, voffB); PG8_STAGE(PG8_SA(1, 0), cA + kstep, voffA); PG8_STAGE(PG8_SB(1, 1), cB + hstepB + kstep, voffB);
;     PG8_WAIT_V(6); PG8_BAR;
;     for (;;) {
;         const bool has_next = S.next(ui + 1, nxt);
;         const char* nA = has_next ? (const char*)g.A + (size_t)nxt.pm * tstepA : cA; const char* nB = has_next ? (const char*)g.Bt + (size_t)nxt.pn * tstepB : cB;
;         for (int t = 0; t < nt; t += 2) {
;             const bool last = (t == nt - 2);
;             const char* a1 = cA + (size_t)(t + 1) * kstep;
;             const char* a2 = last ? nA : cA + (size_t)(t + 2) * kstep; const char* b2 = last ? nB : cB + (size_t)(t + 2) * kstep;
.LBB0_1085:
	s_ashr_i32 s39, s38, 31
	v_cmp_lt_i64_e32 vcc, s[0:1], v[150:151]
	s_lshl_b64 s[0:1], s[38:39], 20
	s_add_u32 s40, s76, s0
	s_addc_u32 s41, s77, s1
	s_and_b64 s[0:1], vcc, exec
	s_cselect_b32 s39, s41, s7
	s_cselect_b32 s59, s40, s6
	s_ashr_i32 s37, s36, 31
	s_lshl_b64 s[0:1], s[36:37], 20
	v_readlane_b32 s42, v253, 28
	v_readlane_b32 s43, v253, 29
	s_add_u32 s42, s42, s0
	s_addc_u32 s43, s43, s1
	s_and_b64 s[0:1], vcc, exec
	s_cselect_b32 s37, s43, s5
	s_cselect_b32 s60, s42, s4
	s_add_u32 s0, s6, 0x80080
	s_addc_u32 s1, s7, 0
	s_add_u32 s61, s4, 0x100
	v_mov_b32_e32 v8, 0
	s_addc_u32 s62, s5, 0
	s_mov_b32 s63, -2
	v_mov_b32_e32 v9, v8
	v_mov_b32_e32 v10, v8
	v_mov_b32_e32 v11, v8
	v_mov_b32_e32 v16, v8
	v_mov_b32_e32 v17, v8
	v_mov_b32_e32 v18, v8
	v_mov_b32_e32 v19, v8
	v_mov_b32_e32 v24, v8
	v_mov_b32_e32 v25, v8
	v_mov_b32_e32 v26, v8
	v_mov_b32_e32 v27, v8
	v_mov_b32_e32 v32, v8
	v_mov_b32_e32 v33, v8
	v_mov_b32_e32 v34, v8
	v_mov_b32_e32 v35, v8
	v_mov_b32_e32 v40, v8
	v_mov_b32_e32 v41, v8
	v_mov_b32_e32 v42, v8
	v_mov_b32_e32 v43, v8
	v_mov_b32_e32 v48, v8
	v_mov_b32_e32 v49, v8
	v_mov_b32_e32 v50, v8
	v_mov_b32_e32 v51, v8
	v_mov_b32_e32 v56, v8
	v_mov_b32_e32 v57, v8
	v_mov_b32_e32 v58, v8
	v_mov_b32_e32 v59, v8
	v_mov_b32_e32 v64, v8
	v_mov_b32_e32 v65, v8
	v_mov_b32_e32 v66, v8
	v_mov_b32_e32 v67, v8
	v_mov_b32_e32 v12, v8
	v_mov_b32_e32 v13, v8
	v_mov_b32_e32 v14, v8
	v_mov_b32_e32 v15, v8
	v_mov_b32_e32 v20, v8
	v_mov_b32_e32 v21, v8
	v_mov_b32_e32 v22, v8
	v_mov_b32_e32 v23, v8
	v_mov_b32_e32 v28, v8
	v_mov_b32_e32 v29, v8
	v_mov_b32_e32 v30, v8
	v_mov_b32_e32 v31, v8
	v_mov_b32_e32 v36, v8
	v_mov_b32_e32 v37, v8
	v_mov_b32_e32 v38, v8
	v_mov_b32_e32 v39, v8
	v_mov_b32_e32 v44, v8
	v_mov_b32_e32 v45, v8
	v_mov_b32_e32 v46, v8
	v_mov_b32_e32 v47, v8
	v_mov_b32_e32 v52, v8
	v_mov_b32_e32 v53, v8
	v_mov_b32_e32 v54, v8
	v_mov_b32_e32 v55, v8
	v_mov_b32_e32 v60, v8
	v_mov_b32_e32 v61, v8
	v_mov_b32_e32 v62, v8
	v_mov_b32_e32 v63, v8
	v_mov_b32_e32 v68, v8
	v_mov_b32_e32 v69, v8
	v_mov_b32_e32 v70, v8
	v_mov_b32_e32 v71, v8
	v_mov_b32_e32 v72, v8
	v_mov_b32_e32 v73, v8
	v_mov_b32_e32 v74, v8
	v_mov_b32_e32 v75, v8
	v_mov_b32_e32 v80, v8
	v_mov_b32_e32 v81, v8
	v_mov_b32_e32 v82, v8
	v_mov_b32_e32 v83, v8
	v_mov_b32_e32 v88, v8
	v_mov_b32_e32 v89, v8
	v_mov_b32_e32 v90, v8
	v_mov_b32_e32 v91, v8
	v_mov_b32_e32 v96, v8
	v_mov_b32_e32 v97, v8
	v_mov_b32_e32 v98, v8
	v_mov_b32_e32 v99, v8
	v_mov_b32_e32 v104, v8
	v_mov_b32_e32 v105, v8
	v_mov_b32_e32 v106, v8
	v_mov_b32_e32 v107, v8
	v_mov_b32_e32 v112, v8
	v_mov_b32_e32 v113, v8
	v_mov_b32_e32 v114, v8
	v_mov_b32_e32 v115, v8
	v_mov_b32_e32 v120, v8
	v_mov_b32_e32 v121, v8
	v_mov_b32_e32 v122, v8
	v_mov_b32_e32 v123, v8
	v_mov_b32_e32 v128, v8
	v_mov_b32_e32 v129, v8
	v_mov_b32_e32 v130, v8
	v_mov_b32_e32 v131, v8
	v_mov_b32_e32 v76, v8
	v_mov_b32_e32 v77, v8
	v_mov_b32_e32 v78, v8
	v_mov_b32_e32 v79, v8
	v_mov_b32_e32 v84, v8
	v_mov_b32_e32 v85, v8
	v_mov_b32_e32 v86, v8
	v_mov_b32_e32 v87, v8
	v_mov_b32_e32 v92, v8
	v_mov_b32_e32 v93, v8
	v_mov_b32_e32 v94, v8
	v_mov_b32_e32 v95, v8
	v_mov_b32_e32 v100, v8
	v_mov_b32_e32 v101, v8
	v_mov_b32_e32 v102, v8
	v_mov_b32_e32 v103, v8
	v_mov_b32_e32 v108, v8
	v_mov_b32_e32 v109, v8
	v_mov_b32_e32 v110, v8
	v_mov_b32_e32 v111, v8
	v_mov_b32_e32 v116, v8
	v_mov_b32_e32 v117, v8
	v_mov_b32_e32 v118, v8
	v_mov_b32_e32 v119, v8
	v_mov_b32_e32 v124, v8
	v_mov_b32_e32 v125, v8
	v_mov_b32_e32 v126, v8
	v_mov_b32_e32 v127, v8
	v_mov_b32_e32 v132, v8
	v_mov_b32_e32 v133, v8
	v_mov_b32_e32 v134, v8
	v_mov_b32_e32 v135, v8
	s_cmp_eq_u32 s101, 0
	s_cbranch_scc0 .Lsp_6
	s_setprio 1

; template <class Epi>
; __device__ __forceinline__ void gemm_phase(PG8_LAS unsigned char* lds, const Gemm g, const StaticOrder& S, const Epi& E) {
;     ...
;     f32x4 acc[2][2][4][2];
; #pragma unroll
;     for (int a = 0; a < 2; ++a)
; #pragma unroll
;         for (int b = 0; b < 2; ++b)
; #pragma unroll
;             for (int m = 0; m < 4; ++m)
; #pragma unroll
;                 for (int n = 0; n < 2; ++n) acc[a][b][m][n] = (f32x4){0.f, 0.f, 0.f, 0.f};
;     ...
;         for (int t = 0; t < nt; t += 2) {
;             const bool last = (t == nt - 2);
;             const char* a1 = cA + (size_t)(t + 1) * kstep;
;             const char* a2 = last ? nA : cA + (size_t)(t + 2) * kstep; const char* b2 = last ? nB : cB + (size_t)(t + 2) * kstep;
.LBB0_1169:
	s_add_u32 s10, s10, 0x160080
	s_addc_u32 s11, s11, 0
	s_add_u32 s36, s12, 0x100
	v_mov_b32_e32 v4, 0
	s_addc_u32 s37, s13, 0
	s_mov_b32 s38, -2
	v_mov_b32_e32 v5, v4
	v_mov_b32_e32 v6, v4
	v_mov_b32_e32 v7, v4
	v_mov_b32_e32 v0, v4
	v_mov_b32_e32 v1, v4
	v_mov_b32_e32 v2, v4
	v_mov_b32_e32 v3, v4
	v_mov_b32_e32 v20, v4
	v_mov_b32_e32 v21, v4
	v_mov_b32_e32 v22, v4
	v_mov_b32_e32 v23, v4
	v_mov_b32_e32 v16, v4
	v_mov_b32_e32 v17, v4
	v_mov_b32_e32 v18, v4
	v_mov_b32_e32 v19, v4
	v_mov_b32_e32 v36, v4
	v_mov_b32_e32 v37, v4
	v_mov_b32_e32 v38, v4
	v_mov_b32_e32 v39, v4
	v_mov_b32_e32 v32, v4
	v_mov_b32_e32 v33, v4
	v_mov_b32_e32 v34, v4
	v_mov_b32_e32 v35, v4
	v_mov_b32_e32 v52, v4
	v_mov_b32_e32 v53, v4
	v_mov_b32_e32 v54, v4
	v_mov_b32_e32 v55, v4
	v_mov_b32_e32 v48, v4
	v_mov_b32_e32 v49, v4
	v_mov_b32_e32 v50, v4
	v_mov_b32_e32 v51, v4
	v_mov_b32_e32 v12, v4
	v_mov_b32_e32 v13, v4
	v_mov_b32_e32 v14, v4
	v_mov_b32_e32 v15, v4
	v_mov_b32_e32 v8, v4
	v_mov_b32_e32 v9, v4
	v_mov_b32_e32 v10, v4
	v_mov_b32_e32 v11, v4
	v_mov_b32_e32 v28, v4
	v_mov_b32_e32 v29, v4
	v_mov_b32_e32 v30, v4
	v_mov_b32_e32 v31, v4
	v_mov_b32_e32 v24, v4
	v_mov_b32_e32 v25, v4
	v_mov_b32_e32 v26, v4
	v_mov_b32_e32 v27, v4
	v_mov_b32_e32 v44, v4
	v_mov_b32_e32 v45, v4
	v_mov_b32_e32 v46, v4
	v_mov_b32_e32 v47, v4
	v_mov_b32_e32 v40, v4
	v_mov_b32_e32 v41, v4
	v_mov_b32_e32 v42, v4
	v_mov_b32_e32 v43, v4
	v_mov_b32_e32 v60, v4
	v_mov_b32_e32 v61, v4
	v_mov_b32_e32 v62, v4
	v_mov_b32_e32 v63, v4
	v_mov_b32_e32 v56, v4
	v_mov_b32_e32 v57, v4
	v_mov_b32_e32 v58, v4
	v_mov_b32_e32 v59, v4
	v_mov_b32_e32 v68, v4
	v_mov_b32_e32 v69, v4
	v_mov_b32_e32 v70, v4
	v_mov_b32_e32 v71, v4
	v_mov_b32_e32 v64, v4
	v_mov_b32_e32 v65, v4
	v_mov_b32_e32 v66, v4
	v_mov_b32_e32 v67, v4
	v_mov_b32_e32 v84, v4
	v_mov_b32_e32 v85, v4
	v_mov_b32_e32 v86, v4
	v_mov_b32_e32 v87, v4
	v_mov_b32_e32 v80, v4
	v_mov_b32_e32 v81, v4
	v_mov_b32_e32 v82, v4
	v_mov_b32_e32 v83, v4
	v_mov_b32_e32 v96, v4
	v_mov_b32_e32 v97, v4
	v_mov_b32_e32 v98, v4
	v_mov_b32_e32 v99, v4
	v_mov_b32_e32 v100, v4
	v_mov_b32_e32 v101, v4
	v_mov_b32_e32 v102, v4
	v_mov_b32_e32 v103, v4
	v_mov_b32_e32 v112, v4
	v_mov_b32_e32 v113, v4
	v_mov_b32_e32 v114, v4
	v_mov_b32_e32 v115, v4
	v_mov_b32_e32 v116, v4
	v_mov_b32_e32 v117, v4
	v_mov_b32_e32 v118, v4
	v_mov_b32_e32 v119, v4
	v_mov_b32_e32 v76, v4
	v_mov_b32_e32 v77, v4
	v_mov_b32_e32 v78, v4
	v_mov_b32_e32 v79, v4
	v_mov_b32_e32 v72, v4
	v_mov_b32_e32 v73, v4
	v_mov_b32_e32 v74, v4
	v_mov_b32_e32 v75, v4
	v_mov_b32_e32 v92, v4
	v_mov_b32_e32 v93, v4
	v_mov_b32_e32 v94, v4
	v_mov_b32_e32 v95, v4
	v_mov_b32_e32 v88, v4
	v_mov_b32_e32 v89, v4
	v_mov_b32_e32 v90, v4
	v_mov_b32_e32 v91, v4
	v_mov_b32_e32 v104, v4
	v_mov_b32_e32 v105, v4
	v_mov_b32_e32 v106, v4
	v_mov_b32_e32 v107, v4
	v_mov_b32_e32 v108, v4
	v_mov_b32_e32 v109, v4
	v_mov_b32_e32 v110, v4
	v_mov_b32_e32 v111, v4
	v_mov_b32_e32 v120, v4
	v_mov_b32_e32 v121, v4
	v_mov_b32_e32 v122, v4
	v_mov_b32_e32 v123, v4
	v_mov_b32_e32 v124, v4
	v_mov_b32_e32 v125, v4
	v_mov_b32_e32 v126, v4
	v_mov_b32_e32 v127, v4
	s_cmp_eq_u32 s101, 0
	s_cbranch_scc0 .Lsp_7
	s_setprio 1
